# ofprep_norm: o_gain loads hoisted out of the row loop
# baseline (speedup 1.0000x reference)
.LBB0_1570:
	s_or_b64 exec, exec, s[0:1]
	v_readlane_b32 s0, v254, 18
	s_waitcnt lgkmcnt(0)
	s_barrier
	v_mov_b32_e32 v1, s0
	v_readlane_b32 s0, v254, 19
	ds_read_b32 v0, v1
	s_nop 0
	v_mov_b32_e32 v2, s0
	ds_read_b32 v3, v2
	s_mov_b32 s2, 0x8800
	s_waitcnt lgkmcnt(0)
	v_readfirstlane_b32 s40, v0
	v_readfirstlane_b32 s41, v3
	ds_read_b32 v0, v1
	ds_read_b32 v3, v2
	s_waitcnt lgkmcnt(0)
	v_readfirstlane_b32 s0, v0
	v_mov_b32_e32 v0, v179
	v_readfirstlane_b32 s1, v3
	s_nop 0
	v_ashrrev_i32_e32 v3, 6, v0
	v_add_u32_e32 v84, s85, v3
	ds_read_b32 v3, v1
	ds_read_b32 v4, v2
	v_cmp_gt_i32_e32 vcc, s2, v84
	s_waitcnt lgkmcnt(0)
	v_readfirstlane_b32 s44, v3
	v_readfirstlane_b32 s45, v4
	ds_read_b32 v3, v1
	ds_read_b32 v4, v2
	ds_read_b32 v1, v1
	ds_read_b32 v2, v2
	s_waitcnt lgkmcnt(0)
	v_readfirstlane_b32 s46, v3
	v_readfirstlane_b32 s47, v4
	v_readfirstlane_b32 s48, v1
	v_readfirstlane_b32 s49, v2
	s_and_saveexec_b64 s[2:3], vcc
	v_readlane_b32 s42, v254, 33
	v_readlane_b32 s43, v254, 34
	s_cbranch_execz .LBB0_1577
	s_lshl_b64 s[50:51], s[56:57], 9
	v_readlane_b32 s52, v250, 0
	v_readlane_b32 s66, v250, 14
	v_readlane_b32 s67, v250, 15
	s_add_u32 s50, s66, s50
	v_lshlrev_b32_e32 v1, 3, v0
	v_lshlrev_b32_e32 v0, 5, v0
	s_addc_u32 s51, s67, s51
	v_and_b32_e32 v176, 0x1e0, v0
	v_and_b32_e32 v2, 0x1f8, v1
	v_lshl_add_u64 v[62:63], s[50:51], 0, v[176:177]
	v_lshlrev_b32_e32 v176, 1, v2
	s_mov_b32 s30, s42
	v_lshl_add_u64 v[0:1], s[44:45], 0, v[176:177]
	s_mov_b64 s[42:43], 0x10d44000
	s_mov_b64 s[44:45], 0x12f44000
	v_lshl_add_u64 v[64:65], v[0:1], 0, s[42:43]
	v_lshl_add_u64 v[66:67], v[0:1], 0, s[44:45]
	v_lshl_add_u64 v[0:1], s[46:47], 0, v[176:177]
	s_mov_b64 s[44:45], 0x17344000
	v_lshl_add_u64 v[68:69], v[0:1], 0, s[44:45]
	v_lshlrev_b32_e32 v0, 2, v2
	v_mov_b32_e32 v1, v177
	v_lshl_add_u64 v[70:71], s[40:41], 0, v[0:1]
	v_lshl_add_u64 v[2:3], s[48:49], 0, v[176:177]
	s_mov_b64 s[40:41], 0x1fd64000
	v_lshl_add_u64 v[72:73], v[2:3], 0, s[40:41]
	v_and_b32_e32 v2, 64, v208
	v_add_u32_e32 v2, 64, v2
	v_xor_b32_e32 v3, 1, v208
	v_cmp_lt_i32_e32 vcc, v3, v2
	v_readlane_b32 s40, v254, 51
	v_readlane_b32 s41, v254, 52
	v_cndmask_b32_e32 v3, v208, v3, vcc
	v_lshlrev_b32_e32 v94, 2, v3
	v_xor_b32_e32 v3, 2, v208
	v_cmp_lt_i32_e32 vcc, v3, v2
	v_lshl_add_u64 v[74:75], s[40:41], 0, v[0:1]
	v_lshl_add_u64 v[78:79], s[92:93], 0, v[0:1]
	v_cndmask_b32_e32 v3, v208, v3, vcc
	v_lshlrev_b32_e32 v95, 2, v3
	v_xor_b32_e32 v3, 4, v208
	v_cmp_lt_i32_e32 vcc, v3, v2
	v_readlane_b32 s53, v250, 1
	v_readlane_b32 s54, v250, 2
	v_cndmask_b32_e32 v3, v208, v3, vcc
	v_lshlrev_b32_e32 v96, 2, v3
	v_xor_b32_e32 v3, 8, v208
	v_cmp_lt_i32_e32 vcc, v3, v2
	v_readlane_b32 s55, v250, 3
	v_readlane_b32 s56, v250, 4
	v_cndmask_b32_e32 v3, v208, v3, vcc
	v_lshlrev_b32_e32 v97, 2, v3
	v_xor_b32_e32 v3, 32, v208
	v_cmp_lt_i32_e32 vcc, v3, v2
	v_readlane_b32 s57, v250, 5
	v_readlane_b32 s58, v250, 6
	v_cndmask_b32_e32 v3, v208, v3, vcc
	v_lshlrev_b32_e32 v98, 2, v3
	v_xor_b32_e32 v3, 16, v208
	v_cmp_lt_i32_e32 vcc, v3, v2
	v_readlane_b32 s59, v250, 7
	v_readlane_b32 s60, v250, 8
	v_cndmask_b32_e32 v2, v208, v3, vcc
	v_lshlrev_b32_e32 v99, 2, v2
	v_or_b32_e32 v2, 0x800, v0
	v_mov_b32_e32 v3, v177
	v_lshl_add_u64 v[0:1], s[0:1], 0, v[176:177]
	s_mov_b64 s[0:1], 0xc944000
	v_lshl_add_u64 v[76:77], s[40:41], 0, v[2:3]
	v_lshl_add_u64 v[80:81], v[0:1], 0, s[0:1]
	s_mov_b64 s[40:41], 0
	v_readlane_b32 s61, v250, 9
	v_readlane_b32 s62, v250, 10
	v_readlane_b32 s63, v250, 11
	v_readlane_b32 s64, v250, 12
	v_readlane_b32 s65, v250, 13
	global_load_dwordx4 v[192:195], v[62:63], off offset:16
	global_load_dwordx4 v[196:199], v[62:63], off
	s_branch .LBB0_1573

.LBB0_1573:
	v_ashrrev_i32_e32 v85, 31, v84
	v_lshlrev_b64 v[0:1], 12, v[84:85]
	v_add_u32_e32 v82, s30, v84
	s_mov_b32 s0, 0x8800
	v_lshl_add_u64 v[0:1], v[70:71], 0, v[0:1]
	v_cmp_gt_i32_e32 vcc, s0, v82
	flat_load_dwordx4 v[28:31], v[0:1]
	flat_load_dwordx4 v[24:27], v[0:1] offset:16
	flat_load_dwordx4 v[20:23], v[0:1] offset:2048
	flat_load_dwordx4 v[16:19], v[0:1] offset:2064
	v_cndmask_b32_e32 v0, v84, v82, vcc
	v_ashrrev_i32_e32 v1, 31, v0
	v_lshlrev_b64 v[2:3], 12, v[0:1]
	v_lshlrev_b64 v[0:1], 10, v[0:1]
	v_lshl_add_u64 v[4:5], v[64:65], 0, v[0:1]
	flat_load_dwordx4 v[40:43], v[4:5]
	v_lshl_add_u64 v[4:5], v[66:67], 0, v[0:1]
	v_lshl_add_u64 v[0:1], v[68:69], 0, v[0:1]
	v_lshlrev_b64 v[86:87], 10, v[84:85]
	flat_load_dwordx4 v[32:35], v[0:1]
	v_lshl_add_u64 v[0:1], v[70:71], 0, v[2:3]
	v_lshl_add_u64 v[48:49], v[66:67], 0, v[86:87]
	flat_load_dwordx4 v[36:39], v[4:5]
	flat_load_dwordx4 v[12:15], v[0:1]
	flat_load_dwordx4 v[8:11], v[0:1] offset:16
	s_nop 0
	flat_load_dwordx4 v[4:7], v[0:1] offset:2048
	s_nop 0
	flat_load_dwordx4 v[0:3], v[0:1] offset:2064
	v_lshl_add_u64 v[44:45], v[68:69], 0, v[86:87]
	flat_load_dwordx4 v[52:55], v[48:49]
	v_lshl_add_u64 v[48:49], v[64:65], 0, v[86:87]
	flat_load_dwordx4 v[56:59], v[48:49]
	v_ashrrev_i32_e32 v83, 31, v82
	flat_load_dwordx4 v[44:47], v[44:45]
	s_waitcnt vmcnt(0) lgkmcnt(0)
	v_lshlrev_b32_e32 v50, 16, v55
	v_and_b32_e32 v51, 0xffff0000, v55
	v_lshlrev_b32_e32 v48, 16, v59
	v_and_b32_e32 v49, 0xffff0000, v59
	v_pk_add_f32 v[88:89], v[50:51], v[48:49]
	v_lshlrev_b32_e32 v48, 16, v58
	v_and_b32_e32 v49, 0xffff0000, v58
	v_lshlrev_b32_e32 v50, 16, v54
	v_and_b32_e32 v51, 0xffff0000, v54
	v_pk_add_f32 v[54:55], v[50:51], v[48:49]
	v_mov_b32_e32 v48, v88
	v_mov_b32_e32 v49, v54
	v_pk_mul_f32 v[48:49], v[48:49], v[48:49]
	v_mov_b32_e32 v50, v89
	v_mov_b32_e32 v51, v55
	v_pk_fma_f32 v[90:91], v[50:51], v[50:51], v[48:49]
	v_mov_b64_e32 v[48:49], v[192:193]
	v_mov_b64_e32 v[50:51], v[194:195]
	v_mov_b64_e32 v[58:59], v[196:197]
	v_mov_b64_e32 v[60:61], v[198:199]
	v_lshlrev_b32_e32 v92, 16, v46
	v_and_b32_e32 v93, 0xffff0000, v46
	v_mul_f32_e32 v46, 0xbfb8aa3b, v92
	v_exp_f32_e32 v46, v46
	v_lshlrev_b32_e32 v102, 16, v53
	v_and_b32_e32 v103, 0xffff0000, v53
	v_add_f32_e32 v46, 1.0, v46
	v_rcp_f32_e32 v100, v46
	v_mul_f32_e32 v46, 0xbfb8aa3b, v93
	v_exp_f32_e32 v46, v46
	s_nop 0
	v_add_f32_e32 v46, 1.0, v46
	v_rcp_f32_e32 v101, v46
	s_nop 0
	v_pk_mul_f32 v[92:93], v[100:101], v[92:93]
	v_lshlrev_b32_e32 v100, 16, v57
	v_and_b32_e32 v101, 0xffff0000, v57
	v_pk_add_f32 v[100:101], v[102:103], v[100:101]
	v_lshlrev_b32_e32 v102, 16, v45
	v_and_b32_e32 v103, 0xffff0000, v45
	v_mul_f32_e32 v45, 0xbfb8aa3b, v102
	v_exp_f32_e32 v45, v45
	v_and_b32_e32 v57, 0xffff0000, v52
	v_add_f32_e32 v45, 1.0, v45
	v_rcp_f32_e32 v104, v45
	v_mul_f32_e32 v45, 0xbfb8aa3b, v103
	v_exp_f32_e32 v45, v45
	s_nop 0
	v_add_f32_e32 v45, 1.0, v45
	v_rcp_f32_e32 v105, v45
	s_nop 0
	v_pk_mul_f32 v[102:103], v[104:105], v[102:103]
	v_lshlrev_b32_e32 v104, 16, v56
	v_and_b32_e32 v105, 0xffff0000, v56
	v_lshlrev_b32_e32 v56, 16, v52
	v_pk_add_f32 v[52:53], v[56:57], v[104:105]
	v_mov_b32_e32 v57, v100
	v_mov_b32_e32 v56, v52
	v_pk_mul_f32 v[56:57], v[56:57], v[56:57]
	v_mov_b32_e32 v104, v53
	v_mov_b32_e32 v105, v101
	v_pk_fma_f32 v[56:57], v[104:105], v[104:105], v[56:57]
	v_lshlrev_b32_e32 v104, 16, v44
	v_add_f32_e32 v46, v56, v57
	v_add_f32_e32 v46, v91, v46
	v_add_f32_e32 v46, v90, v46
	ds_bpermute_b32 v56, v94, v46
	v_and_b32_e32 v105, 0xffff0000, v44
	v_mul_f32_e32 v44, 0xbfb8aa3b, v104
	v_mul_f32_e32 v45, 0xbfb8aa3b, v105
	v_exp_f32_e32 v44, v44
	s_waitcnt lgkmcnt(0)
	v_add_f32_e32 v46, v46, v56
	ds_bpermute_b32 v56, v95, v46
	v_exp_f32_e32 v45, v45
	v_add_f32_e32 v44, 1.0, v44
	v_rcp_f32_e32 v44, v44
	s_waitcnt lgkmcnt(0)
	v_add_f32_e32 v46, v46, v56
	ds_bpermute_b32 v56, v96, v46
	v_add_f32_e32 v45, 1.0, v45
	v_rcp_f32_e32 v45, v45
	s_waitcnt lgkmcnt(0)
	v_add_f32_e32 v46, v46, v56
	ds_bpermute_b32 v56, v97, v46
	v_pk_mul_f32 v[44:45], v[44:45], v[104:105]
	s_waitcnt lgkmcnt(0)
	v_add_f32_e32 v46, v46, v56
	v_fmamk_f32 v46, v46, 0x3c000000, v191
	v_cmp_gt_f32_e64 s[0:1], s81, v46
	v_mul_f32_e32 v56, 0x4b800000, v46
	s_nop 0
	v_cndmask_b32_e64 v46, v46, v56, s[0:1]
	v_rsq_f32_e32 v46, v46
	s_nop 0
	v_mul_f32_e32 v56, 0x45800000, v46
	v_cndmask_b32_e64 v56, v46, v56, s[0:1]
	v_pk_mul_f32 v[54:55], v[54:55], v[56:57] op_sel_hi:[1,0]
	v_lshlrev_b32_e32 v46, 16, v47
	v_and_b32_e32 v47, 0xffff0000, v47
	s_waitcnt vmcnt(1)
	v_pk_mul_f32 v[48:49], v[48:49], v[54:55]
	v_mul_f32_e32 v54, 0xbfb8aa3b, v46
	v_mul_f32_e32 v55, 0xbfb8aa3b, v47
	v_exp_f32_e32 v54, v54
	v_exp_f32_e32 v55, v55
	v_pk_mul_f32 v[52:53], v[52:53], v[56:57] op_sel_hi:[1,0]
	v_pk_mul_f32 v[48:49], v[92:93], v[48:49]
	v_add_f32_e32 v54, 1.0, v54
	v_add_f32_e32 v55, 1.0, v55
	v_rcp_f32_e32 v54, v54
	v_rcp_f32_e32 v55, v55
	s_waitcnt vmcnt(0)
	v_pk_mul_f32 v[52:53], v[58:59], v[52:53]
	v_pk_mul_f32 v[46:47], v[54:55], v[46:47]
	v_pk_mul_f32 v[44:45], v[44:45], v[52:53]
	v_pk_mul_f32 v[52:53], v[100:101], v[56:57] op_sel_hi:[1,0]
	v_pk_mul_f32 v[56:57], v[88:89], v[56:57] op_sel_hi:[1,0]
	v_pk_mul_f32 v[52:53], v[60:61], v[52:53]
	v_pk_mul_f32 v[50:51], v[50:51], v[56:57]
	v_pk_mul_f32 v[52:53], v[102:103], v[52:53]
	v_pk_mul_f32 v[50:51], v[46:47], v[50:51]
	v_cvt_pk_bf16_f32 v44, v44, v45
	v_cvt_pk_bf16_f32 v45, v52, v53
	v_cvt_pk_bf16_f32 v46, v48, v49
	v_cvt_pk_bf16_f32 v47, v50, v51
	v_lshl_add_u64 v[48:49], v[72:73], 0, v[86:87]
	flat_store_dwordx4 v[48:49], v[44:47]
	s_and_saveexec_b64 s[0:1], vcc
	s_cbranch_execz .LBB0_1575
	v_lshlrev_b32_e32 v44, 16, v43
	v_and_b32_e32 v45, 0xffff0000, v43
	v_lshlrev_b32_e32 v46, 16, v39
	v_and_b32_e32 v47, 0xffff0000, v39
	v_pk_add_f32 v[50:51], v[44:45], v[46:47]
	v_lshlrev_b32_e32 v44, 16, v42
	v_and_b32_e32 v45, 0xffff0000, v42
	v_lshlrev_b32_e32 v42, 16, v38
	v_and_b32_e32 v43, 0xffff0000, v38
	v_pk_add_f32 v[38:39], v[44:45], v[42:43]
	v_mov_b32_e32 v42, v50
	v_mov_b32_e32 v43, v38
	v_pk_mul_f32 v[42:43], v[42:43], v[42:43]
	v_mov_b32_e32 v44, v51
	v_mov_b32_e32 v45, v39
	v_pk_fma_f32 v[52:53], v[44:45], v[44:45], v[42:43]
	v_mov_b64_e32 v[42:43], v[192:193]
	v_mov_b64_e32 v[44:45], v[194:195]
	v_mov_b64_e32 v[46:47], v[196:197]
	v_mov_b64_e32 v[48:49], v[198:199]
	v_lshlrev_b32_e32 v54, 16, v34
	v_and_b32_e32 v55, 0xffff0000, v34
	v_mul_f32_e32 v34, 0xbfb8aa3b, v54
	v_exp_f32_e32 v34, v34
	v_lshlrev_b32_e32 v58, 16, v37
	v_and_b32_e32 v59, 0xffff0000, v37
	v_add_f32_e32 v34, 1.0, v34
	v_rcp_f32_e32 v56, v34
	v_mul_f32_e32 v34, 0xbfb8aa3b, v55
	v_exp_f32_e32 v34, v34
	s_nop 0
	v_add_f32_e32 v34, 1.0, v34
	v_rcp_f32_e32 v57, v34
	s_nop 0
	v_pk_mul_f32 v[54:55], v[56:57], v[54:55]
	v_lshlrev_b32_e32 v56, 16, v41
	v_and_b32_e32 v57, 0xffff0000, v41
	v_pk_add_f32 v[56:57], v[56:57], v[58:59]
	v_lshlrev_b32_e32 v58, 16, v33
	v_and_b32_e32 v59, 0xffff0000, v33
	v_mul_f32_e32 v33, 0xbfb8aa3b, v58
	v_exp_f32_e32 v33, v33
	v_and_b32_e32 v41, 0xffff0000, v36
	v_add_f32_e32 v33, 1.0, v33
	v_rcp_f32_e32 v60, v33
	v_mul_f32_e32 v33, 0xbfb8aa3b, v59
	v_exp_f32_e32 v33, v33
	s_nop 0
	v_add_f32_e32 v33, 1.0, v33
	v_rcp_f32_e32 v61, v33
	s_nop 0
	v_pk_mul_f32 v[58:59], v[60:61], v[58:59]
	v_lshlrev_b32_e32 v60, 16, v40
	v_and_b32_e32 v61, 0xffff0000, v40
	v_lshlrev_b32_e32 v40, 16, v36
	v_pk_add_f32 v[36:37], v[60:61], v[40:41]
	v_mov_b32_e32 v41, v56
	v_mov_b32_e32 v40, v36
	v_pk_mul_f32 v[40:41], v[40:41], v[40:41]
	v_mov_b32_e32 v60, v37
	v_mov_b32_e32 v61, v57
	v_pk_fma_f32 v[40:41], v[60:61], v[60:61], v[40:41]
	v_lshlrev_b32_e32 v60, 16, v32
	v_add_f32_e32 v34, v40, v41
	v_add_f32_e32 v34, v53, v34
	v_add_f32_e32 v34, v52, v34
	ds_bpermute_b32 v40, v94, v34
	v_and_b32_e32 v61, 0xffff0000, v32
	v_mul_f32_e32 v32, 0xbfb8aa3b, v60
	v_mul_f32_e32 v33, 0xbfb8aa3b, v61
	v_exp_f32_e32 v32, v32
	s_waitcnt lgkmcnt(0)
	v_add_f32_e32 v34, v34, v40
	ds_bpermute_b32 v40, v95, v34
	v_exp_f32_e32 v33, v33
	v_add_f32_e32 v32, 1.0, v32
	v_rcp_f32_e32 v32, v32
	v_and_b32_e32 v41, 0xffff0000, v35
	s_waitcnt lgkmcnt(0)
	v_add_f32_e32 v34, v34, v40
	ds_bpermute_b32 v40, v96, v34
	v_add_f32_e32 v33, 1.0, v33
	v_rcp_f32_e32 v33, v33
	s_waitcnt lgkmcnt(0)
	v_add_f32_e32 v34, v34, v40
	ds_bpermute_b32 v40, v97, v34
	v_pk_mul_f32 v[32:33], v[32:33], v[60:61]
	s_waitcnt lgkmcnt(0)
	v_add_f32_e32 v34, v34, v40
	v_fmamk_f32 v34, v34, 0x3c000000, v191
	v_cmp_gt_f32_e32 vcc, s81, v34
	v_mul_f32_e32 v40, 0x4b800000, v34
	s_nop 0
	v_cndmask_b32_e32 v34, v34, v40, vcc
	v_rsq_f32_e32 v34, v34
	s_nop 0
	v_mul_f32_e32 v40, 0x45800000, v34
	v_cndmask_b32_e32 v34, v34, v40, vcc
	v_pk_mul_f32 v[36:37], v[36:37], v[34:35] op_sel_hi:[1,0]
	v_pk_mul_f32 v[38:39], v[38:39], v[34:35] op_sel_hi:[1,0]
	s_waitcnt vmcnt(0)
	v_pk_mul_f32 v[36:37], v[46:47], v[36:37]
	v_lshlrev_b32_e32 v40, 16, v35
	v_pk_mul_f32 v[32:33], v[32:33], v[36:37]
	v_pk_mul_f32 v[36:37], v[56:57], v[34:35] op_sel_hi:[1,0]
	v_pk_mul_f32 v[38:39], v[42:43], v[38:39]
	v_mul_f32_e32 v35, 0xbfb8aa3b, v40
	v_mul_f32_e32 v43, 0xbfb8aa3b, v41
	v_exp_f32_e32 v35, v35
	v_exp_f32_e32 v43, v43
	v_pk_mul_f32 v[36:37], v[48:49], v[36:37]
	v_pk_mul_f32 v[38:39], v[54:55], v[38:39]
	v_add_f32_e32 v35, 1.0, v35
	v_add_f32_e32 v43, 1.0, v43
	v_rcp_f32_e32 v42, v35
	v_rcp_f32_e32 v43, v43
	v_pk_mul_f32 v[34:35], v[50:51], v[34:35] op_sel_hi:[1,0]
	v_pk_mul_f32 v[36:37], v[58:59], v[36:37]
	v_pk_mul_f32 v[34:35], v[44:45], v[34:35]
	v_pk_mul_f32 v[40:41], v[42:43], v[40:41]
	v_cvt_pk_bf16_f32 v32, v32, v33
	v_pk_mul_f32 v[40:41], v[40:41], v[34:35]
	v_cvt_pk_bf16_f32 v33, v36, v37
	v_lshlrev_b64 v[36:37], 10, v[82:83]
	v_cvt_pk_bf16_f32 v34, v38, v39
	v_cvt_pk_bf16_f32 v35, v40, v41
	v_lshl_add_u64 v[36:37], v[72:73], 0, v[36:37]
	flat_store_dwordx4 v[36:37], v[32:35]
